# static priority raise: waves 4-7 run the prompt-attention interval loops at s_setprio 1 (set once per pass), reset after the prompt units
# baseline (speedup 1.0000x reference)
; #define NSA_POP(REM_) ((REM_) ? (t_ = sel ? __builtin_ctzll(REM_) : 63 - __builtin_clzll(REM_), (REM_) &= ~(1ull << t_), t_) : -1)
; __device__ __forceinline__ void nsa_prompt_unit(Frame& F, int l, int b, int kvh, int c) {
;     ...
;     for (int pass = 0; pass < 2; ++pass) {
;         const bool sel = pass == 0;
;         flash_reset(S);
;         const bf16_t* kb = (const bf16_t*)(F.ws + (sel ? WS_KTSEL : WS_KTWIN)) + (size_t)(b * 4 + kvh) * 64 * 4096;
;         const bf16_t* vt = (const bf16_t*)(F.ws + (sel ? WS_VTSEL : WS_VTWIN)) + (size_t)(b * 4 + kvh) * 64 * 4096;
;         unsigned long long rem;
;         if (sel) rem = ((unsigned long long)uhi << 32) | ulo;
;         else { const int lo = c >= 8 ? c - 8 : 0; rem = (c == 63 ? ~0ull : ((1ull << (c + 1)) - 1ull)) & ~((1ull << lo) - 1ull); }
;         int t_;
;         int tA = NSA_POP(rem), tB = NSA_POP(rem);
;         int pr = 0; bool first = true;
;         __syncthreads();
;         tile_dma(kb + (size_t)tA * 4096, vt + (size_t)tA * 4096, F.lds, w, lane);
;         if (tB >= 0) tile_dma(kb + (size_t)tB * 4096, vt + (size_t)tB * 4096, F.lds + AL_SLOT, w, lane);
.LBB0_846:
	s_cmp_lt_u32 s40, 0x1000
	s_cbranch_scc1 .Lattprio_skip
	s_setprio 1

; __device__ __forceinline__ void nsa_sample_unit(Frame& F, int l, int unit, int part_id) {
;     const int tid = F.tid, qi = unit & 3, kvh = (unit >> 2) & 3, b = unit >> 4, row = MPT + b * 4 + qi;
;     const bf16_t* P = (const bf16_t*)(F.ws + WS_P); const int* pt = (const int*)FIN(IN_PT);
;     LAS float* qv = (LAS float*)(F.lds + SL_Q); LAS float* sc = (LAS float*)(F.lds + SL_SC); LAS float* imp = (LAS float*)(F.lds + SL_IMP); LAS float* red = (LAS float*)(F.lds + SL_RED);
;     LAS int* list = (LAS int*)(F.lds + SL_LIST); LAS int* koff = (LAS int*)(F.lds + SL_KOFF); LAS float* part = (LAS float*)(F.lds + SL_PART); LAS float* oacc = (LAS float*)(F.lds + SL_OACC);
;     LAS int* ptl = (LAS int*)(F.lds + SL_PT);
;     __syncthreads();
;     if (part_id == 0 && tid >= 256 && tid < 384) ptl[tid - 256] = pt[b * 128 + tid - 256];
;     if (tid < 256) qv[tid] = bf2f(P[(size_t)row * NPROJ + C_Q + kvh * 256 + tid]) * (1.f / SM_SCALE_L2E);
;     __syncthreads();
;     float* soacc = (float*)(F.ws + WS_SOACC) + (size_t)unit * 768;
;     if (part_id == 0) {
;     {
;         const int n = tid & 255, gp = tid >> 8;
;         const bf16_t* kr = (const bf16_t*)(F.ws + WS_KCS) + ((size_t)(b * 4 + kvh) * 256 + n) * 64;
;         float d0 = 0.f, d1 = 0.f;
; #pragma unroll
;         for (int j = 0; j < 8; ++j) { const u32x4 x = *(const u32x4*)(kr + 8 * j); float kf[8]; unpack8(x, kf);
; #pragma unroll
;             for (int e = 0; e < 8; ++e) { d0 += kf[e] * qv[(2 * gp) * 64 + 8 * j + e]; d1 += kf[e] * qv[(2 * gp + 1) * 64 + 8 * j + e]; } }
;         sc[(2 * gp) * 1040 + n] = d0 * 0.125f; sc[(2 * gp + 1) * 1040 + n] = d1 * 0.125f;
;     }
;     __syncthreads();
;     block_softmax4(sc, 256, red, tid);
;     if (tid < 257) { float v; if (tid == 0 || tid >= 255) v = 1e4f; else v = sc[tid] + sc[1040 + tid] + sc[2080 + tid] + sc[3120 + tid]; imp[tid] = v; }
;     {
;         const int half = tid >> 8, gd = tid & 255, gh = gd >> 6, d = gd & 63;
;         const bf16_t* vt = (const bf16_t*)(F.ws + WS_VCTS) + (size_t)(b * 4 + kvh) * 4 * 4096;
;         float a = 0.f;
;         for (int tl = 2 * half; tl < 2 * half + 2; ++tl) {
;             const bf16_t* vr = vt + (size_t)tl * 4096 + d * 64;
; #pragma unroll
;             for (int j = 0; j < 8; ++j) { const u32x4 x = *(const u32x4*)(vr + 8 * j); float vf[8]; unpack8(x, vf);
; #pragma unroll
.LBB0_876:
	s_setprio 0
	v_readlane_b32 s16, v252, 0
	v_readlane_b32 s17, v252, 1
	v_readlane_b32 s18, v252, 2
	v_readlane_b32 s19, v252, 3
	v_mov_b32_e32 v96, v0
	s_mov_b64 s[20:21], s[18:19]
	s_mov_b64 s[14:15], s[16:17]
	v_readlane_b32 s16, v255, 11
	v_readlane_b32 s17, v255, 12
	s_and_b64 vcc, exec, s[16:17]
	v_readlane_b32 s14, v255, 1
	s_movk_i32 s81, 0x100
	s_movk_i32 s92, 0x1ff
	s_movk_i32 s93, 0x200
	v_readlane_b32 s15, v255, 2
	s_cbranch_vccnz .LBB0_1093
	v_ashrrev_i32_e32 v2, 6, v96
	v_readlane_b32 s16, v255, 6
	v_lshl_add_u32 v132, v2, 2, 0
	v_mov_b32_e32 v2, 7
	v_readlane_b32 s17, v255, 7
	v_lshlrev_b32_sdwa v98, v2, v96 dst_sel:DWORD dst_unused:UNUSED_PAD src0_sel:DWORD src1_sel:BYTE_0
	s_lshl_b32 s15, s16, 12
	v_lshl_add_u64 v[2:3], s[20:21], 0, v[98:99]
	s_mov_b64 s[16:17], 0x20400000
	v_ashrrev_i32_e32 v4, 8, v96
	v_lshl_add_u64 v[106:107], v[2:3], 0, s[16:17]
	v_mov_b32_e32 v3, 2
	v_mul_i32_i24_e32 v2, 0x2080, v4
	v_lshlrev_b32_sdwa v3, v3, v96 dst_sel:DWORD dst_unused:UNUSED_PAD src0_sel:DWORD src1_sel:BYTE_0
	v_lshlrev_b32_e32 v10, 9, v4
	s_waitcnt vmcnt(0)
	v_add3_u32 v137, 0, v2, v3
	v_lshlrev_b32_e32 v2, 1, v4
	v_lshlrev_b32_e32 v4, 7, v96
	v_and_b32_e32 v98, 0x1f80, v4
	s_movk_i32 s8, 0x1040
	v_bfe_u32 v3, v96, 6, 2
	v_lshl_add_u64 v[4:5], s[20:21], 0, v[98:99]
	s_mov_b64 s[16:17], 0x20500000
	v_lshl_add_u64 v[108:109], v[4:5], 0, s[16:17]
	v_mad_u32_u24 v4, v3, s8, 0
	v_ashrrev_i32_e32 v3, 31, v2
	v_lshlrev_b32_e32 v105, 2, v96
	v_lshlrev_b64 v[110:111], 13, v[2:3]
	v_or_b32_e32 v2, 1, v2
	v_ashrrev_i32_e32 v8, 4, v96
	v_and_b32_e32 v104, 60, v105
	v_ashrrev_i32_e32 v3, 31, v2
	s_movk_i32 s4, 0x204
	v_lshlrev_b32_e32 v9, 10, v8
	v_lshlrev_b64 v[112:113], 13, v[2:3]
	v_lshl_add_u32 v139, v2, 8, v4
	v_lshlrev_b32_e32 v2, 2, v104
	v_and_b32_e32 v1, 0xffffff80, v96
	v_cmp_gt_i32_e64 s[46:47], s4, v96
	s_movk_i32 s4, 0x203
	v_add3_u32 v140, 0, v9, v2
	v_max_i32_e32 v2, 4, v96
	v_cmp_eq_u32_e64 s[42:43], s81, v1
	v_cmp_lt_i32_e64 s[48:49], s4, v96
	v_ashrrev_i32_e32 v1, 7, v96
	s_movk_i32 s4, 0xefc8
	v_sub_u32_e32 v2, v2, v96
	s_add_u32 s40, s20, 0xc800000
	v_mul_lo_u32 v133, v1, s4
	v_lshl_add_u32 v134, v8, 4, v8
	s_movk_i32 s4, 0x101
	v_add_u32_e32 v2, 0x1ff, v2
	s_addc_u32 s41, s21, 0
	v_mul_lo_u32 v7, v1, s8
	v_min_i32_e32 v1, 0x1f3, v134
	v_cmp_gt_i32_e64 s[54:55], s4, v96
	s_movk_i32 s4, 0xff
	v_lshrrev_b32_e32 v3, 9, v2
	s_add_u32 s30, s20, 0x2b600000
	v_add_u32_e32 v135, 17, v1
	v_cmp_ne_u32_e32 vcc, 0, v96
	v_cmp_gt_i32_e64 s[56:57], s4, v96
	s_movk_i32 s4, 0x400
	v_add_u32_e32 v3, 1, v3
	v_sub_u32_e32 v1, v1, v134
	s_addc_u32 s31, s21, 0
	v_and_b32_e32 v6, 0x7f, v96
	s_and_b64 s[18:19], vcc, s[56:57]
	v_add_u32_e32 v138, v4, v10
	v_cmp_gt_i32_e64 s[56:57], s4, v96
	v_add_u32_e32 v4, 1, v1
	v_and_b32_e32 v141, 0xfffffe, v3
	v_readlane_b32 s4, v254, 55
	v_cmp_lt_u32_e64 s[60:61], s92, v2
	v_cmp_ne_u32_e64 s[16:17], v3, v141
	v_and_b32_e32 v143, 7, v4
	v_add_u32_e32 v144, s4, v105
	s_add_i32 s4, 0, 0x400
	v_lshlrev_b32_e32 v2, 2, v6
	s_movk_i32 s8, 0x44
	v_ashrrev_i32_e32 v97, 31, v96
	v_and_b32_e32 v131, 63, v96
	v_add_u32_e32 v5, 16, v1
	v_writelane_b32 v255, s16, 13
	v_add3_u32 v147, v7, v2, s4
	v_mul_lo_u32 v2, v8, s8
	v_lshlrev_b32_e32 v3, 2, v143
	v_readlane_b32 s8, v254, 56
	v_add_u32_e32 v115, 0, v105
	v_cmp_gt_i32_e64 s[44:45], s81, v96
	v_lshl_add_u64 v[102:103], v[96:97], 1, s[40:41]
	v_add_u32_e32 v130, 0, v7
	v_cmp_eq_u32_e64 s[50:51], 0, v131
	v_cmp_lt_i32_e64 s[52:53], v134, v135
	v_add_u32_e32 v136, 0, v10
	v_cmp_gt_i32_e64 s[58:59], 32, v8
	v_lshl_add_u32 v142, v141, 9, v96
	v_mov_b32_e32 v114, v96
	v_mov_b32_e32 v1, v96
	v_add_u32_e32 v117, 0x200, v96
	v_mov_b32_e32 v116, v96
	v_writelane_b32 v255, s17, 14
	v_cmp_ne_u32_e64 s[64:65], 0, v143
	v_cmp_lt_u32_e64 s[66:67], 6, v5
	v_add_u32_e32 v145, s4, v105
	v_add_u32_e32 v146, 0xfffffe00, v96
	v_or_b32_e32 v148, 0xffffff80, v6
	v_add_u32_e32 v149, s4, v2
	v_add_u32_e32 v150, v134, v143
	v_add3_u32 v151, v2, v3, s4
	v_add_u32_e32 v152, s8, v105
	v_lshl_add_u32 v153, v8, 7, s4
	s_mov_b32 s34, s14
	s_mov_b32 s35, s14
	s_branch .LBB0_880
